# GEMM1 epilogue: direct branch to the silu/gate block per row-group for heavy tile types (skips the per-group type-dispatch branch chain)
# speedup vs baseline: 1.0229x; 1.0004x over previous
; __device__ __forceinline__ u32x4 pk8(f32x4 a, f32x4 b) { u32x4 w; w.x = pk2(a[0], a[1]); w.y = pk2(a[2], a[3]); w.z = pk2(b[0], b[1]); w.w = pk2(b[2], b[3]); return w; }
;     __device__ __forceinline__ void operator()(const AccT& acc, const Unit& u, int wr, int wc, int fr_, int fq_) const {
;     ...
;         const int pn = u.pn < 8 ? u.pn : u.pn + 8, cb = wc * 32 + 8 * fq;
;         bf16_t* const U = (bf16_t*)(ws + WS_RB); bf16_t* const A2 = (bf16_t*)(ws + WS_A2); bf16_t* const QL = (bf16_t*)(ws + WS_QL); bf16_t* const KVL = (bf16_t*)(ws + WS_KVL); bf16_t* const KPE = (bf16_t*)(ws + WS_KPE);
;         bf16_t* const R = (bf16_t*)out; bf16_t* const SB = (bf16_t*)out + (size_t)T * 1024; float* const ssq_q = (float*)(ws + WS_SSQ); float* const ssq_kv = ssq_q + T; const float* const rope = (const float*)(ws + WS_ROPE);
; #pragma unroll
;         for (int ai = 0; ai < 2; ++ai)
; #pragma unroll
;             for (int m = 0; m < 4; ++m) {
;                 const size_t row = (size_t)ROW_OF(ai, m);
;                 const f32x4 a0 = acc[ai][0][m][0], a1 = acc[ai][0][m][1], b0 = acc[ai][1][m][0], b1 = acc[ai][1][m][1];
;                 if (pn < 8) {
;                     st16c(U + row * 1024 + pn * 128 + cb, pk8(a0 * b0, a1 * b1));
;                 } else if (pn == 16) {
;                     st16c(QL + row * 384 + cb, pk8(a0, a1)); st16c(QL + row * 384 + 128 + cb, pk8(b0, b1));
;                     float s = (sumsq4(a0) + sumsq4(a1)) + (sumsq4(b0) + sumsq4(b1));
;                     s += __shfl_xor(s, 16); s += __shfl_xor(s, 32);
;                     if (fq == 0) atomicAdd(ssq_q + row, s);
;                 } else if (pn == 17) {
;                     st16c(QL + row * 384 + 256 + cb, pk8(a0, a1)); st16c(KVL + row * 256 + cb, pk8(b0, b1));
;                     float s = sumsq4(a0) + sumsq4(a1), s2 = sumsq4(b0) + sumsq4(b1);
;                     s += __shfl_xor(s, 16); s += __shfl_xor(s, 32); s2 += __shfl_xor(s2, 16); s2 += __shfl_xor(s2, 32);
;                     if (fq == 0) { atomicAdd(ssq_q + row, s); atomicAdd(ssq_kv + row, s2); }
;                 } else if (pn == 18) {
;                     if (wc < 2) {
;     ...
;                 } else if (pn < 23) {
;                     bf16_t* p = A2 + row * 2048 + 1024 + (pn - 19) * 256 + cb;
;                     st16(p, pk8(silu4(a0), silu4(a1))); st16(p + 128, pk8(silu4(b0), silu4(b1)));
;                 } else {
.LBB0_359:
	s_add_i32 s4, s10, 8
	s_cmp_lt_i32 s10, 8
	s_cselect_b32 s82, s10, s4
	s_cmp_lg_u32 s82, 18
	s_cselect_b32 s99, 1, 0
	s_cmp_gt_i32 s82, 7
	s_cselect_b64 s[10:11], -1, 0
	s_cmp_gt_u32 s82, 22
	s_cselect_b64 s[48:49], -1, 0
	s_lshl_b32 s6, s82, 7
	s_add_i32 s16, s6, 0xfffff480
	s_lshl_b64 s[46:47], s[16:17], 1
	v_mov_b32_e32 v136, v201
	v_mov_b32_e32 v150, v232
	s_add_u32 s50, s88, s46
	s_addc_u32 s51, s89, s47
	v_lshl_add_u32 v148, v150, 3, s67
	v_lshlrev_b32_e32 v146, 4, v150
	v_ashrrev_i32_e32 v149, 31, v148
	s_add_u32 s46, s71, s46
	v_ashrrev_i32_e32 v147, 31, v146
	v_lshlrev_b64 v[160:161], 1, v[148:149]
	s_addc_u32 s47, s72, s47
	s_lshl_b32 s7, s82, 9
	v_lshl_add_u64 v[158:159], v[146:147], 2, s[36:37]
	v_lshlrev_b32_e32 v146, 8, v150
	v_cmp_eq_u32_e64 s[4:5], 0, v150
	v_lshl_add_u64 v[150:151], s[46:47], 0, v[160:161]
	s_add_u32 s46, s90, s7
	s_addc_u32 s47, s91, 0
	s_ashr_i32 s7, s6, 31
	s_lshl_b64 s[6:7], s[6:7], 1
	s_add_u32 s6, s69, s6
	s_addc_u32 s7, s70, s7
	s_lshl_b32 s16, s33, 8
	s_add_i32 s16, s16, s66
	v_and_b32_e32 v175, 0x100, v146
	v_and_b32_e32 v156, 0xfffffe00, v146
	v_add_u32_e32 v146, s16, v136
	v_ashrrev_i32_e32 v157, 31, v156
	v_lshl_add_u64 v[154:155], s[28:29], 0, v[160:161]
	v_lshl_add_u64 v[152:153], s[50:51], 0, v[160:161]
	v_ashrrev_i32_e32 v147, 31, v146
	s_mov_b64 s[50:51], -1
	s_and_b64 vcc, exec, s[10:11]
	s_cbranch_vccz .LBB0_391
	s_cmp_gt_u32 s82, 18
	s_cbranch_scc1 .LBB0_382
	s_mov_b64 s[54:55], -1
	s_mov_b64 s[50:51], 0
	s_cmp_lt_i32 s82, 17
	s_mov_b64 s[52:53], 0
	s_cbranch_scc0 .LBB0_364
	s_and_b64 vcc, exec, s[54:55]
	s_cbranch_vccnz .LBB0_381

; __device__ __forceinline__ u32x4 pk8(f32x4 a, f32x4 b) { u32x4 w; w.x = pk2(a[0], a[1]); w.y = pk2(a[2], a[3]); w.z = pk2(b[0], b[1]); w.w = pk2(b[2], b[3]); return w; }
; __device__ __forceinline__ float sumsq4(f32x4 x) { return (x[0] * x[0] + x[1] * x[1]) + (x[2] * x[2] + x[3] * x[3]); }
;     __device__ __forceinline__ void operator()(const AccT& acc, const Unit& u, int wr, int wc, int fr_, int fq_) const {
;     ...
;             for (int m = 0; m < 4; ++m) {
;                 const size_t row = (size_t)ROW_OF(ai, m);
;                 const f32x4 a0 = acc[ai][0][m][0], a1 = acc[ai][0][m][1], b0 = acc[ai][1][m][0], b1 = acc[ai][1][m][1];
;                 if (pn < 8) {
;                     st16c(U + row * 1024 + pn * 128 + cb, pk8(a0 * b0, a1 * b1));
;                 } else if (pn == 16) {
;                     st16c(QL + row * 384 + cb, pk8(a0, a1)); st16c(QL + row * 384 + 128 + cb, pk8(b0, b1));
;                     float s = (sumsq4(a0) + sumsq4(a1)) + (sumsq4(b0) + sumsq4(b1));
;                     s += __shfl_xor(s, 16); s += __shfl_xor(s, 32);
;                     if (fq == 0) atomicAdd(ssq_q + row, s);
;                 } else if (pn == 17) {
;                     st16c(QL + row * 384 + 256 + cb, pk8(a0, a1)); st16c(KVL + row * 256 + cb, pk8(b0, b1));
;                     float s = sumsq4(a0) + sumsq4(a1), s2 = sumsq4(b0) + sumsq4(b1);
;                     s += __shfl_xor(s, 16); s += __shfl_xor(s, 32); s2 += __shfl_xor(s2, 16); s2 += __shfl_xor(s2, 32);
;                     if (fq == 0) { atomicAdd(ssq_q + row, s); atomicAdd(ssq_kv + row, s2); }
;                 } else if (pn == 18) {
;                     if (wc < 2) {
;     ...
;                 } else if (pn < 23) {
.LBB0_393:
	s_nop 1
	v_add_u32_e32 v112, 16, v146
	v_cndmask_b32_e64 v114, 0, 1, s[10:11]
	v_ashrrev_i32_e32 v113, 31, v112
	v_cmp_ne_u32_e64 s[6:7], 1, v114
	s_andn2_b64 vcc, exec, s[10:11]
	s_mov_b64 s[10:11], -1
	s_cbranch_vccnz .LBB0_425
	s_cmp_gt_u32 s82, 18
	s_cbranch_scc1 .LBB0_416
	s_mov_b64 s[52:53], -1
	s_mov_b64 s[10:11], 0
	s_cmp_lt_i32 s82, 17
	s_mov_b64 s[50:51], 0
	s_cbranch_scc0 .LBB0_398
	s_and_b64 vcc, exec, s[52:53]
	s_cbranch_vccnz .LBB0_415

; __device__ __forceinline__ u32x4 pk8(f32x4 a, f32x4 b) { u32x4 w; w.x = pk2(a[0], a[1]); w.y = pk2(a[2], a[3]); w.z = pk2(b[0], b[1]); w.w = pk2(b[2], b[3]); return w; }
; __device__ __forceinline__ float sumsq4(f32x4 x) { return (x[0] * x[0] + x[1] * x[1]) + (x[2] * x[2] + x[3] * x[3]); }
;     __device__ __forceinline__ void operator()(const AccT& acc, const Unit& u, int wr, int wc, int fr_, int fq_) const {
;     ...
;             for (int m = 0; m < 4; ++m) {
;                 const size_t row = (size_t)ROW_OF(ai, m);
;                 const f32x4 a0 = acc[ai][0][m][0], a1 = acc[ai][0][m][1], b0 = acc[ai][1][m][0], b1 = acc[ai][1][m][1];
;                 if (pn < 8) {
;                     st16c(U + row * 1024 + pn * 128 + cb, pk8(a0 * b0, a1 * b1));
;                 } else if (pn == 16) {
;                     st16c(QL + row * 384 + cb, pk8(a0, a1)); st16c(QL + row * 384 + 128 + cb, pk8(b0, b1));
;                     float s = (sumsq4(a0) + sumsq4(a1)) + (sumsq4(b0) + sumsq4(b1));
;                     s += __shfl_xor(s, 16); s += __shfl_xor(s, 32);
;                     if (fq == 0) atomicAdd(ssq_q + row, s);
;                 } else if (pn == 17) {
;                     st16c(QL + row * 384 + 256 + cb, pk8(a0, a1)); st16c(KVL + row * 256 + cb, pk8(b0, b1));
;                     float s = sumsq4(a0) + sumsq4(a1), s2 = sumsq4(b0) + sumsq4(b1);
;                     s += __shfl_xor(s, 16); s += __shfl_xor(s, 32); s2 += __shfl_xor(s2, 16); s2 += __shfl_xor(s2, 32);
;                     if (fq == 0) { atomicAdd(ssq_q + row, s); atomicAdd(ssq_kv + row, s2); }
;                 } else if (pn == 18) {
;                     if (wc < 2) {
;     ...
;                 } else if (pn < 23) {
.LBB0_427:
	s_nop 1
	v_add_u32_e32 v96, 32, v146
	v_ashrrev_i32_e32 v97, 31, v96
	s_and_b64 vcc, exec, s[6:7]
	s_mov_b64 s[10:11], -1
	s_cbranch_vccnz .LBB0_459
	s_cmp_gt_u32 s82, 18
	s_cbranch_scc1 .LBB0_450
	s_mov_b64 s[52:53], -1
	s_mov_b64 s[10:11], 0
	s_cmp_lt_i32 s82, 17
	s_mov_b64 s[50:51], 0
	s_cbranch_scc0 .LBB0_432
	s_and_b64 vcc, exec, s[52:53]
	s_cbranch_vccnz .LBB0_449

; __device__ __forceinline__ u32x4 pk8(f32x4 a, f32x4 b) { u32x4 w; w.x = pk2(a[0], a[1]); w.y = pk2(a[2], a[3]); w.z = pk2(b[0], b[1]); w.w = pk2(b[2], b[3]); return w; }
; __device__ __forceinline__ float sumsq4(f32x4 x) { return (x[0] * x[0] + x[1] * x[1]) + (x[2] * x[2] + x[3] * x[3]); }
;     __device__ __forceinline__ void operator()(const AccT& acc, const Unit& u, int wr, int wc, int fr_, int fq_) const {
;     ...
;             for (int m = 0; m < 4; ++m) {
;                 const size_t row = (size_t)ROW_OF(ai, m);
;                 const f32x4 a0 = acc[ai][0][m][0], a1 = acc[ai][0][m][1], b0 = acc[ai][1][m][0], b1 = acc[ai][1][m][1];
;                 if (pn < 8) {
;                     st16c(U + row * 1024 + pn * 128 + cb, pk8(a0 * b0, a1 * b1));
;                 } else if (pn == 16) {
;                     st16c(QL + row * 384 + cb, pk8(a0, a1)); st16c(QL + row * 384 + 128 + cb, pk8(b0, b1));
;                     float s = (sumsq4(a0) + sumsq4(a1)) + (sumsq4(b0) + sumsq4(b1));
;                     s += __shfl_xor(s, 16); s += __shfl_xor(s, 32);
;                     if (fq == 0) atomicAdd(ssq_q + row, s);
;                 } else if (pn == 17) {
;                     st16c(QL + row * 384 + 256 + cb, pk8(a0, a1)); st16c(KVL + row * 256 + cb, pk8(b0, b1));
;                     float s = sumsq4(a0) + sumsq4(a1), s2 = sumsq4(b0) + sumsq4(b1);
;                     s += __shfl_xor(s, 16); s += __shfl_xor(s, 32); s2 += __shfl_xor(s2, 16); s2 += __shfl_xor(s2, 32);
;                     if (fq == 0) { atomicAdd(ssq_q + row, s); atomicAdd(ssq_kv + row, s2); }
;                 } else if (pn == 18) {
;                     if (wc < 2) {
;     ...
;                 } else if (pn < 23) {
.LBB0_461:
	s_nop 1
	v_add_u32_e32 v80, 48, v146
	v_ashrrev_i32_e32 v81, 31, v80
	s_and_b64 vcc, exec, s[6:7]
	s_mov_b64 s[10:11], -1
	s_cbranch_vccnz .LBB0_493
	s_cmp_gt_u32 s82, 18
	s_cbranch_scc1 .LBB0_484
	s_mov_b64 s[52:53], -1
	s_mov_b64 s[10:11], 0
	s_cmp_lt_i32 s82, 17
	s_mov_b64 s[50:51], 0
	s_cbranch_scc0 .LBB0_466
	s_and_b64 vcc, exec, s[52:53]
	s_cbranch_vccnz .LBB0_483

; __device__ __forceinline__ u32x4 pk8(f32x4 a, f32x4 b) { u32x4 w; w.x = pk2(a[0], a[1]); w.y = pk2(a[2], a[3]); w.z = pk2(b[0], b[1]); w.w = pk2(b[2], b[3]); return w; }
; __device__ __forceinline__ float sumsq4(f32x4 x) { return (x[0] * x[0] + x[1] * x[1]) + (x[2] * x[2] + x[3] * x[3]); }
;     __device__ __forceinline__ void operator()(const AccT& acc, const Unit& u, int wr, int wc, int fr_, int fq_) const {
;     ...
;             for (int m = 0; m < 4; ++m) {
;                 const size_t row = (size_t)ROW_OF(ai, m);
;                 const f32x4 a0 = acc[ai][0][m][0], a1 = acc[ai][0][m][1], b0 = acc[ai][1][m][0], b1 = acc[ai][1][m][1];
;                 if (pn < 8) {
;                     st16c(U + row * 1024 + pn * 128 + cb, pk8(a0 * b0, a1 * b1));
;                 } else if (pn == 16) {
;                     st16c(QL + row * 384 + cb, pk8(a0, a1)); st16c(QL + row * 384 + 128 + cb, pk8(b0, b1));
;                     float s = (sumsq4(a0) + sumsq4(a1)) + (sumsq4(b0) + sumsq4(b1));
;                     s += __shfl_xor(s, 16); s += __shfl_xor(s, 32);
;                     if (fq == 0) atomicAdd(ssq_q + row, s);
;                 } else if (pn == 17) {
;                     st16c(QL + row * 384 + 256 + cb, pk8(a0, a1)); st16c(KVL + row * 256 + cb, pk8(b0, b1));
;                     float s = sumsq4(a0) + sumsq4(a1), s2 = sumsq4(b0) + sumsq4(b1);
;                     s += __shfl_xor(s, 16); s += __shfl_xor(s, 32); s2 += __shfl_xor(s2, 16); s2 += __shfl_xor(s2, 32);
;                     if (fq == 0) { atomicAdd(ssq_q + row, s); atomicAdd(ssq_kv + row, s2); }
;                 } else if (pn == 18) {
;                     if (wc < 2) {
;     ...
;                 } else if (pn < 23) {
.LBB0_495:
	s_nop 1
	v_add_u32_e32 v64, 0x80, v146
	v_ashrrev_i32_e32 v65, 31, v64
	s_and_b64 vcc, exec, s[6:7]
	s_mov_b64 s[10:11], -1
	s_cbranch_vccnz .LBB0_527
	s_cmp_gt_u32 s82, 18
	s_cbranch_scc1 .LBB0_518
	s_mov_b64 s[52:53], -1
	s_mov_b64 s[10:11], 0
	s_cmp_lt_i32 s82, 17
	s_mov_b64 s[50:51], 0
	s_cbranch_scc0 .LBB0_500
	s_and_b64 vcc, exec, s[52:53]
	s_cbranch_vccnz .LBB0_517

; __device__ __forceinline__ u32x4 pk8(f32x4 a, f32x4 b) { u32x4 w; w.x = pk2(a[0], a[1]); w.y = pk2(a[2], a[3]); w.z = pk2(b[0], b[1]); w.w = pk2(b[2], b[3]); return w; }
; __device__ __forceinline__ float sumsq4(f32x4 x) { return (x[0] * x[0] + x[1] * x[1]) + (x[2] * x[2] + x[3] * x[3]); }
;     __device__ __forceinline__ void operator()(const AccT& acc, const Unit& u, int wr, int wc, int fr_, int fq_) const {
;     ...
;             for (int m = 0; m < 4; ++m) {
;                 const size_t row = (size_t)ROW_OF(ai, m);
;                 const f32x4 a0 = acc[ai][0][m][0], a1 = acc[ai][0][m][1], b0 = acc[ai][1][m][0], b1 = acc[ai][1][m][1];
;                 if (pn < 8) {
;                     st16c(U + row * 1024 + pn * 128 + cb, pk8(a0 * b0, a1 * b1));
;                 } else if (pn == 16) {
;                     st16c(QL + row * 384 + cb, pk8(a0, a1)); st16c(QL + row * 384 + 128 + cb, pk8(b0, b1));
;                     float s = (sumsq4(a0) + sumsq4(a1)) + (sumsq4(b0) + sumsq4(b1));
;                     s += __shfl_xor(s, 16); s += __shfl_xor(s, 32);
;                     if (fq == 0) atomicAdd(ssq_q + row, s);
;                 } else if (pn == 17) {
;                     st16c(QL + row * 384 + 256 + cb, pk8(a0, a1)); st16c(KVL + row * 256 + cb, pk8(b0, b1));
;                     float s = sumsq4(a0) + sumsq4(a1), s2 = sumsq4(b0) + sumsq4(b1);
;                     s += __shfl_xor(s, 16); s += __shfl_xor(s, 32); s2 += __shfl_xor(s2, 16); s2 += __shfl_xor(s2, 32);
;                     if (fq == 0) { atomicAdd(ssq_q + row, s); atomicAdd(ssq_kv + row, s2); }
;                 } else if (pn == 18) {
;                     if (wc < 2) {
;     ...
;                 } else if (pn < 23) {
.LBB0_529:
	s_nop 1
	v_add_u32_e32 v48, 0x90, v146
	v_ashrrev_i32_e32 v49, 31, v48
	s_and_b64 vcc, exec, s[6:7]
	s_mov_b64 s[10:11], -1
	s_cbranch_vccnz .LBB0_561
	s_cmp_gt_u32 s82, 18
	s_cbranch_scc1 .LBB0_552
	s_mov_b64 s[52:53], -1
	s_mov_b64 s[10:11], 0
	s_cmp_lt_i32 s82, 17
	s_mov_b64 s[50:51], 0
	s_cbranch_scc0 .LBB0_534
	s_and_b64 vcc, exec, s[52:53]
	s_cbranch_vccnz .LBB0_551

; __device__ __forceinline__ u32x4 pk8(f32x4 a, f32x4 b) { u32x4 w; w.x = pk2(a[0], a[1]); w.y = pk2(a[2], a[3]); w.z = pk2(b[0], b[1]); w.w = pk2(b[2], b[3]); return w; }
; __device__ __forceinline__ float sumsq4(f32x4 x) { return (x[0] * x[0] + x[1] * x[1]) + (x[2] * x[2] + x[3] * x[3]); }
;     __device__ __forceinline__ void operator()(const AccT& acc, const Unit& u, int wr, int wc, int fr_, int fq_) const {
;     ...
;             for (int m = 0; m < 4; ++m) {
;                 const size_t row = (size_t)ROW_OF(ai, m);
;                 const f32x4 a0 = acc[ai][0][m][0], a1 = acc[ai][0][m][1], b0 = acc[ai][1][m][0], b1 = acc[ai][1][m][1];
;                 if (pn < 8) {
;                     st16c(U + row * 1024 + pn * 128 + cb, pk8(a0 * b0, a1 * b1));
;                 } else if (pn == 16) {
;                     st16c(QL + row * 384 + cb, pk8(a0, a1)); st16c(QL + row * 384 + 128 + cb, pk8(b0, b1));
;                     float s = (sumsq4(a0) + sumsq4(a1)) + (sumsq4(b0) + sumsq4(b1));
;                     s += __shfl_xor(s, 16); s += __shfl_xor(s, 32);
;                     if (fq == 0) atomicAdd(ssq_q + row, s);
;                 } else if (pn == 17) {
;                     st16c(QL + row * 384 + 256 + cb, pk8(a0, a1)); st16c(KVL + row * 256 + cb, pk8(b0, b1));
;                     float s = sumsq4(a0) + sumsq4(a1), s2 = sumsq4(b0) + sumsq4(b1);
;                     s += __shfl_xor(s, 16); s += __shfl_xor(s, 32); s2 += __shfl_xor(s2, 16); s2 += __shfl_xor(s2, 32);
;                     if (fq == 0) { atomicAdd(ssq_q + row, s); atomicAdd(ssq_kv + row, s2); }
;                 } else if (pn == 18) {
;                     if (wc < 2) {
;     ...
;                 } else if (pn < 23) {
.LBB0_563:
	s_nop 1
	v_add_u32_e32 v32, 0xa0, v146
	v_ashrrev_i32_e32 v33, 31, v32
	s_and_b64 vcc, exec, s[6:7]
	s_mov_b64 s[10:11], -1
	s_cbranch_vccnz .LBB0_595
	s_cmp_gt_u32 s82, 18
	s_cbranch_scc1 .LBB0_586
	s_mov_b64 s[52:53], -1
	s_mov_b64 s[10:11], 0
	s_cmp_lt_i32 s82, 17
	s_mov_b64 s[50:51], 0
	s_cbranch_scc0 .LBB0_568
	s_and_b64 vcc, exec, s[52:53]
	s_cbranch_vccnz .LBB0_585
